# grid barrier: last arriver of each XCD adds to the release word directly (no returning TOP atomic); all leaders poll it for nxcd*(gen+1)
# speedup vs baseline: 1.0043x; 1.0043x over previous
.LBB0_147:
	s_or_b64 exec, exec, s[14:15]
	v_cvt_f32_u32_e32 v4, v2
	s_waitcnt vmcnt(0)
	v_readfirstlane_b32 s3, v3
	v_sub_u32_e32 v3, 0, v2
	v_rcp_iflag_f32_e32 v4, v4
	v_add_u32_e32 v5, s3, v1
	v_mul_f32_e32 v4, 0x4f7ffffe, v4
	v_cvt_u32_f32_e32 v4, v4
	v_mul_lo_u32 v1, v3, v4
	v_mul_hi_u32 v1, v4, v1
	v_add_u32_e32 v1, v4, v1
	v_mul_hi_u32 v1, v5, v1
	v_mul_lo_u32 v3, v1, v2
	v_sub_u32_e32 v3, v5, v3
	v_add_u32_e32 v4, 1, v1
	v_cmp_ge_u32_e32 vcc, v3, v2
	s_nop 1
	v_cndmask_b32_e32 v1, v1, v4, vcc
	v_sub_u32_e32 v4, v3, v2
	v_cndmask_b32_e32 v3, v3, v4, vcc
	v_add_u32_e32 v4, 1, v1
	v_cmp_ge_u32_e32 vcc, v3, v2
	v_add_u32_e32 v3, 1, v5
	s_nop 0
	v_cndmask_b32_e32 v1, v1, v4, vcc
	v_mul_lo_u32 v4, v2, v1
	v_add_u32_e32 v2, v4, v2
	v_cmp_ne_u32_e32 vcc, v3, v2
	s_waitcnt lgkmcnt(0)
	s_cbranch_vccnz .Lbk0_poll
	buffer_wbl2 sc1
	s_waitcnt vmcnt(0)
	v_mov_b32_e32 v6, 0x3600
	v_mov_b32_e32 v7, 1
	global_atomic_add v6, v7, s[42:43]
.Lbk0_poll:
	v_add_u32_e32 v7, 1, v1
	v_mul_lo_u32 v7, v7, v0
	v_mov_b32_e32 v6, 0x3600
	s_mov_b32 s98, 0
.Lbk0_loop:
	global_load_dword v8, v6, s[42:43] sc1
	s_add_i32 s98, s98, 1
	s_waitcnt vmcnt(0)
	v_cmp_lt_u32_e32 vcc, v8, v7
	s_cbranch_vccz .Lbk0_done
	s_cmp_lt_u32 s98, 0x400000
	s_cbranch_scc0 .Lbk0_done
	s_sleep 1
	s_branch .Lbk0_loop
.Lbk0_done:
	s_branch .LBB0_181
.Lseam0_aux:
	s_or_b64 exec, exec, s[8:9]
	v_readfirstlane_b32 s98, v213
	s_nop 3
	s_lshr_b32 s98, s98, 6
	s_cmp_lg_u32 s98, 1
	s_cbranch_scc1 .LBB0_181
	buffer_inv sc1
	s_waitcnt vmcnt(0)

.LBB0_374:
	s_or_b64 exec, exec, s[14:15]
	v_cvt_f32_u32_e32 v4, v2
	s_waitcnt vmcnt(0)
	v_readfirstlane_b32 s3, v3
	v_sub_u32_e32 v3, 0, v2
	v_rcp_iflag_f32_e32 v4, v4
	v_add_u32_e32 v5, s3, v1
	v_mul_f32_e32 v4, 0x4f7ffffe, v4
	v_cvt_u32_f32_e32 v4, v4
	v_mul_lo_u32 v1, v3, v4
	v_mul_hi_u32 v1, v4, v1
	v_add_u32_e32 v1, v4, v1
	v_mul_hi_u32 v1, v5, v1
	v_mul_lo_u32 v3, v1, v2
	v_sub_u32_e32 v3, v5, v3
	v_add_u32_e32 v4, 1, v1
	v_cmp_ge_u32_e32 vcc, v3, v2
	s_nop 1
	v_cndmask_b32_e32 v1, v1, v4, vcc
	v_sub_u32_e32 v4, v3, v2
	v_cndmask_b32_e32 v3, v3, v4, vcc
	v_add_u32_e32 v4, 1, v1
	v_cmp_ge_u32_e32 vcc, v3, v2
	v_add_u32_e32 v3, 1, v5
	s_nop 0
	v_cndmask_b32_e32 v1, v1, v4, vcc
	v_mul_lo_u32 v4, v2, v1
	v_add_u32_e32 v2, v4, v2
	v_cmp_ne_u32_e32 vcc, v3, v2
	s_waitcnt lgkmcnt(0)
	s_cbranch_vccnz .Lbk1_poll
	v_mov_b32_e32 v6, 0x3600
	v_mov_b32_e32 v7, 1
	global_atomic_add v6, v7, s[42:43]

.Lbk1_done:
	s_branch .LBB0_408
.Lseam1_aux:
	s_or_b64 exec, exec, s[8:9]
	v_readfirstlane_b32 s98, v213
	s_nop 3
	s_lshr_b32 s98, s98, 6
	s_cmp_lg_u32 s98, 1
	s_cbranch_scc1 .LBB0_408
	buffer_inv sc1
	s_waitcnt vmcnt(0)

.Lbk2_done:
	s_branch .LBB0_534
.Lseam2_aux:
	s_or_b64 exec, exec, s[8:9]
	v_readfirstlane_b32 s98, v213
	s_nop 3
	s_lshr_b32 s98, s98, 6
	s_cmp_lg_u32 s98, 1
	s_cbranch_scc1 .LBB0_534
	buffer_inv sc1
	s_waitcnt vmcnt(0)

.Lbk3_done:
	s_branch .LBB0_604
.Lseam3_aux:
	s_or_b64 exec, exec, s[6:7]
	v_readfirstlane_b32 s98, v213
	s_nop 3
	s_lshr_b32 s98, s98, 6
	s_cmp_lg_u32 s98, 1
	s_cbranch_scc1 .LBB0_604
	buffer_inv sc1
	s_waitcnt vmcnt(0)

.Lbk4_done:
	s_branch .LBB0_681
.Lseam4_aux:
	s_or_b64 exec, exec, s[8:9]
	v_readfirstlane_b32 s98, v213
	s_nop 3
	s_lshr_b32 s98, s98, 6
	s_cmp_lg_u32 s98, 1
	s_cbranch_scc1 .LBB0_681
	buffer_inv sc1
	s_waitcnt vmcnt(0)

.Lbk5_done:
	s_branch .LBB0_752
.Lseam5_aux:
	s_or_b64 exec, exec, s[8:9]
	v_readfirstlane_b32 s98, v213
	s_nop 3
	s_lshr_b32 s98, s98, 6
	s_cmp_lg_u32 s98, 1
	s_cbranch_scc1 .LBB0_752
	buffer_inv sc1
	s_waitcnt vmcnt(0)

.Lbk6_done:
	s_branch .LBB0_811
.Lseam6_aux:
	s_or_b64 exec, exec, s[6:7]
	v_readfirstlane_b32 s98, v213
	s_nop 3
	s_lshr_b32 s98, s98, 6
	s_cmp_lg_u32 s98, 1
	s_cbranch_scc1 .LBB0_811
	buffer_inv sc1
	s_waitcnt vmcnt(0)

.Lbk7_done:
	s_branch .LBB0_964
.Lseam7_aux:
	s_or_b64 exec, exec, s[8:9]
	v_readfirstlane_b32 s98, v213
	s_nop 3
	s_lshr_b32 s98, s98, 6
	s_cmp_lg_u32 s98, 1
	s_cbranch_scc1 .LBB0_964
	buffer_inv sc1
	s_waitcnt vmcnt(0)

.Lbk8_done:
	s_branch .LBB0_1029
.Lseam8_aux:
	s_or_b64 exec, exec, s[8:9]
	v_readfirstlane_b32 s98, v213
	s_nop 3
	s_lshr_b32 s98, s98, 6
	s_cmp_lg_u32 s98, 1
	s_cbranch_scc1 .LBB0_1029
	buffer_inv sc1
	s_waitcnt vmcnt(0)

.Lbk9_done:
	s_branch .LBB0_1217
.LBB0_1192:
	s_movk_i32 s71, 0x900
	s_mov_b64 s[36:37], 0
	s_mov_b64 s[30:31], s[16:17]
	s_mov_b64 s[6:7], s[14:15]
	s_mov_b64 s[28:29], s[12:13]
	s_andn2_b64 vcc, exec, s[38:39]
	s_cbranch_vccz .LBB0_1040
	s_branch .LBB0_1041
.Lseam9_aux:
	s_or_b64 exec, exec, s[8:9]
	v_readfirstlane_b32 s98, v213
	s_nop 3
	s_lshr_b32 s98, s98, 6
	s_cmp_lg_u32 s98, 1
	s_cbranch_scc1 .LBB0_1217
	buffer_inv sc1
	s_waitcnt vmcnt(0)

.Lbk10_done:
	s_branch .LBB0_1416
.Lseam10_aux:
	s_or_b64 exec, exec, s[8:9]
	v_readfirstlane_b32 s98, v213
	s_nop 3
	s_lshr_b32 s98, s98, 6
	s_cmp_lg_u32 s98, 1
	s_cbranch_scc1 .LBB0_1416
	buffer_inv sc1
	s_waitcnt vmcnt(0)

.LBB0_1453:
	s_or_b64 exec, exec, s[12:13]
	v_cvt_f32_u32_e32 v4, v2
	s_waitcnt vmcnt(0)
	v_readfirstlane_b32 s3, v3
	v_sub_u32_e32 v3, 0, v2
	v_rcp_iflag_f32_e32 v4, v4
	v_add_u32_e32 v5, s3, v1
	v_mul_f32_e32 v4, 0x4f7ffffe, v4
	v_cvt_u32_f32_e32 v4, v4
	v_mul_lo_u32 v1, v3, v4
	v_mul_hi_u32 v1, v4, v1
	v_add_u32_e32 v1, v4, v1
	v_mul_hi_u32 v1, v5, v1
	v_mul_lo_u32 v3, v1, v2
	v_sub_u32_e32 v3, v5, v3
	v_add_u32_e32 v4, 1, v1
	v_cmp_ge_u32_e32 vcc, v3, v2
	s_nop 1
	v_cndmask_b32_e32 v1, v1, v4, vcc
	v_sub_u32_e32 v4, v3, v2
	v_cndmask_b32_e32 v3, v3, v4, vcc
	v_add_u32_e32 v4, 1, v1
	v_cmp_ge_u32_e32 vcc, v3, v2
	v_add_u32_e32 v3, 1, v5
	s_nop 0
	v_cndmask_b32_e32 v1, v1, v4, vcc
	v_mul_lo_u32 v4, v2, v1
	v_add_u32_e32 v2, v4, v2
	v_cmp_ne_u32_e32 vcc, v3, v2
	s_waitcnt lgkmcnt(0)
	s_cbranch_vccnz .Lbk11_poll
	v_mov_b32_e32 v6, 0x3600
	v_mov_b32_e32 v7, 1
	global_atomic_add v6, v7, s[42:43]

.Lbk11_done:
	s_branch .LBB0_1487
.Lseam11_aux:
	s_or_b64 exec, exec, s[8:9]
	v_readfirstlane_b32 s98, v213
	s_nop 3
	s_lshr_b32 s98, s98, 6
	s_cmp_lg_u32 s98, 1
	s_cbranch_scc1 .LBB0_1487
	buffer_inv sc1
	s_waitcnt vmcnt(0)
